# gate pre-activation rewrite (chained fma_mix, no dead denorm path) in both GLA variants + batched w3 loads + gemv 16 loads in flight
# speedup vs baseline: 1.0060x; 1.0060x over previous
.LBB0_1203:
	s_or_b64 exec, exec, s[14:15]
	v_mov_b32_e32 v92, v2
	s_mov_b64 s[16:17], -1
	v_and_b32_e32 v93, 3, v92
	v_lshrrev_b32_e32 v94, 6, v92
	v_and_or_b32 v93, v94, s61, v93
	v_mul_lo_u32 v93, v93, s2
	v_lshrrev_b32_e32 v92, 1, v92
	v_add_u32_e32 v93, 0, v93
	v_and_b32_e32 v94, 0x60, v92
	v_and_b32_e32 v92, 30, v92
	v_add3_u32 v92, v93, v94, v92
	ds_write_b16 v92, v88 offset:35840
	ds_write_b16_d16_hi v92, v88 offset:35984
	ds_write_b16 v92, v89 offset:36128
	ds_write_b16_d16_hi v92, v89 offset:36272
	ds_write_b16 v92, v90 offset:36416
	ds_write_b16_d16_hi v92, v90 offset:36560
	ds_write_b16 v92, v91 offset:36704
	ds_write_b16_d16_hi v92, v91 offset:36848
	v_mov_b32_e32 v88, v2
	s_nop 0
	v_add_u32_e32 v89, 0x200, v88
	v_and_b32_e32 v90, 3, v88
	v_lshrrev_b32_e32 v89, 6, v89
	v_and_or_b32 v89, v89, s61, v90
	v_mul_lo_u32 v89, v89, s2
	v_lshrrev_b32_e32 v88, 1, v88
	v_add_u32_e32 v89, 0, v89
	v_and_b32_e32 v90, 0x60, v88
	v_and_b32_e32 v88, 30, v88
	v_add3_u32 v88, v89, v90, v88
	ds_write_b16 v88, v84 offset:35840
	ds_write_b16_d16_hi v88, v84 offset:35984
	ds_write_b16 v88, v85 offset:36128
	ds_write_b16_d16_hi v88, v85 offset:36272
	ds_write_b16 v88, v86 offset:36416
	ds_write_b16_d16_hi v88, v86 offset:36560
	ds_write_b16 v88, v87 offset:36704
	ds_write_b16_d16_hi v88, v87 offset:36848
	v_mov_b32_e32 v84, v2
	s_nop 0
	v_add_u32_e32 v85, 0x400, v84
	v_and_b32_e32 v86, 3, v84
	v_lshrrev_b32_e32 v85, 6, v85
	v_and_or_b32 v85, v85, s61, v86
	v_mul_lo_u32 v85, v85, s2
	v_lshrrev_b32_e32 v84, 1, v84
	v_add_u32_e32 v85, 0, v85
	v_and_b32_e32 v86, 0x60, v84
	v_and_b32_e32 v84, 30, v84
	v_add3_u32 v84, v85, v86, v84
	ds_write_b16 v84, v76 offset:35840
	ds_write_b16_d16_hi v84, v76 offset:35984
	ds_write_b16 v84, v77 offset:36128
	ds_write_b16_d16_hi v84, v77 offset:36272
	ds_write_b16 v84, v78 offset:36416
	ds_write_b16_d16_hi v84, v78 offset:36560
	ds_write_b16 v84, v79 offset:36704
	ds_write_b16_d16_hi v84, v79 offset:36848
	v_mov_b32_e32 v76, v2
	s_nop 0
	v_add_u32_e32 v77, 0x600, v76
	v_and_b32_e32 v78, 3, v76
	v_lshrrev_b32_e32 v77, 6, v77
	v_and_or_b32 v77, v77, s61, v78
	v_mul_lo_u32 v77, v77, s2
	v_lshrrev_b32_e32 v76, 1, v76
	v_add_u32_e32 v77, 0, v77
	v_and_b32_e32 v78, 0x60, v76
	v_and_b32_e32 v76, 30, v76
	v_add3_u32 v76, v77, v78, v76
	ds_write_b16 v76, v68 offset:35840
	ds_write_b16_d16_hi v76, v68 offset:35984
	ds_write_b16 v76, v69 offset:36128
	ds_write_b16_d16_hi v76, v69 offset:36272
	ds_write_b16 v76, v70 offset:36416
	ds_write_b16_d16_hi v76, v70 offset:36560
	ds_write_b16 v76, v71 offset:36704
	ds_write_b16_d16_hi v76, v71 offset:36848
	v_and_b32_e32 v68, 0x78, v120
	v_lshl_add_u32 v68, v68, 1, s3
	v_lshrrev_b32_e32 v69, 4, v2
	v_add_u32_e32 v2, 0x200, v2
	v_mad_u64_u32 v[70:71], s[10:11], v69, s72, v[68:69]
	v_lshrrev_b32_e32 v2, 4, v2
	ds_write_b128 v70, v[72:75]
	v_mad_u64_u32 v[68:69], s[10:11], v2, s72, v[68:69]
	v_mov_b32_e32 v72, v99
	v_mov_b32_e32 v2, v119
	ds_write_b128 v68, v[80:83]
	s_waitcnt lgkmcnt(0)
	s_barrier
	s_nop 0
	v_lshl_add_u32 v240, v2, 10, s38
	ds_read_b128 v[200:203], v240
	ds_read_b128 v[206:209], v240 offset:16
	ds_read_b128 v[210:213], v240 offset:64
	ds_read_b128 v[214:217], v240 offset:80
	ds_read_b128 v[218:221], v240 offset:128
	ds_read_b128 v[224:227], v240 offset:144
	ds_read_b128 v[232:235], v240 offset:192
	ds_read_b128 v[236:239], v240 offset:208
	s_waitcnt lgkmcnt(0)
	v_fma_mix_f32 v73, v101, v200, v100 op_sel_hi:[0,1,0]
	v_fma_mix_f32 v69, v101, v210, v100 op_sel_hi:[0,1,0]
	v_fma_mix_f32 v70, v101, v218, v100 op_sel_hi:[0,1,0]
	v_fma_mix_f32 v71, v101, v232, v100 op_sel_hi:[0,1,0]
	v_fma_mix_f32 v73, v109, v206, v73 op_sel_hi:[0,1,0]
	v_fma_mix_f32 v69, v109, v214, v69 op_sel_hi:[0,1,0]
	v_fma_mix_f32 v70, v109, v224, v70 op_sel_hi:[0,1,0]
	v_fma_mix_f32 v71, v109, v236, v71 op_sel_hi:[0,1,0]
	v_fma_mix_f32 v73, v102, v200, v73 op_sel:[0,1,0] op_sel_hi:[0,1,0]
	v_fma_mix_f32 v69, v102, v210, v69 op_sel:[0,1,0] op_sel_hi:[0,1,0]
	v_fma_mix_f32 v70, v102, v218, v70 op_sel:[0,1,0] op_sel_hi:[0,1,0]
	v_fma_mix_f32 v71, v102, v232, v71 op_sel:[0,1,0] op_sel_hi:[0,1,0]
	v_fma_mix_f32 v73, v110, v206, v73 op_sel:[0,1,0] op_sel_hi:[0,1,0]
	v_fma_mix_f32 v69, v110, v214, v69 op_sel:[0,1,0] op_sel_hi:[0,1,0]
	v_fma_mix_f32 v70, v110, v224, v70 op_sel:[0,1,0] op_sel_hi:[0,1,0]
	v_fma_mix_f32 v71, v110, v236, v71 op_sel:[0,1,0] op_sel_hi:[0,1,0]
	v_fma_mix_f32 v73, v103, v201, v73 op_sel_hi:[0,1,0]
	v_fma_mix_f32 v69, v103, v211, v69 op_sel_hi:[0,1,0]
	v_fma_mix_f32 v70, v103, v219, v70 op_sel_hi:[0,1,0]
	v_fma_mix_f32 v71, v103, v233, v71 op_sel_hi:[0,1,0]
	v_fma_mix_f32 v73, v111, v207, v73 op_sel_hi:[0,1,0]
	v_fma_mix_f32 v69, v111, v215, v69 op_sel_hi:[0,1,0]
	v_fma_mix_f32 v70, v111, v225, v70 op_sel_hi:[0,1,0]
	v_fma_mix_f32 v71, v111, v237, v71 op_sel_hi:[0,1,0]
	v_fma_mix_f32 v73, v104, v201, v73 op_sel:[0,1,0] op_sel_hi:[0,1,0]
	v_fma_mix_f32 v69, v104, v211, v69 op_sel:[0,1,0] op_sel_hi:[0,1,0]
	v_fma_mix_f32 v70, v104, v219, v70 op_sel:[0,1,0] op_sel_hi:[0,1,0]
	v_fma_mix_f32 v71, v104, v233, v71 op_sel:[0,1,0] op_sel_hi:[0,1,0]
	v_fma_mix_f32 v73, v112, v207, v73 op_sel:[0,1,0] op_sel_hi:[0,1,0]
	v_fma_mix_f32 v69, v112, v215, v69 op_sel:[0,1,0] op_sel_hi:[0,1,0]
	v_fma_mix_f32 v70, v112, v225, v70 op_sel:[0,1,0] op_sel_hi:[0,1,0]
	v_fma_mix_f32 v71, v112, v237, v71 op_sel:[0,1,0] op_sel_hi:[0,1,0]
	v_fma_mix_f32 v73, v105, v202, v73 op_sel_hi:[0,1,0]
	v_fma_mix_f32 v69, v105, v212, v69 op_sel_hi:[0,1,0]
	v_fma_mix_f32 v70, v105, v220, v70 op_sel_hi:[0,1,0]
	v_fma_mix_f32 v71, v105, v234, v71 op_sel_hi:[0,1,0]
	v_fma_mix_f32 v73, v114, v208, v73 op_sel_hi:[0,1,0]
	v_fma_mix_f32 v69, v114, v216, v69 op_sel_hi:[0,1,0]
	v_fma_mix_f32 v70, v114, v226, v70 op_sel_hi:[0,1,0]
	v_fma_mix_f32 v71, v114, v238, v71 op_sel_hi:[0,1,0]
	v_fma_mix_f32 v73, v106, v202, v73 op_sel:[0,1,0] op_sel_hi:[0,1,0]
	v_fma_mix_f32 v69, v106, v212, v69 op_sel:[0,1,0] op_sel_hi:[0,1,0]
	v_fma_mix_f32 v70, v106, v220, v70 op_sel:[0,1,0] op_sel_hi:[0,1,0]
	v_fma_mix_f32 v71, v106, v234, v71 op_sel:[0,1,0] op_sel_hi:[0,1,0]
	v_fma_mix_f32 v73, v116, v208, v73 op_sel:[0,1,0] op_sel_hi:[0,1,0]
	v_fma_mix_f32 v69, v116, v216, v69 op_sel:[0,1,0] op_sel_hi:[0,1,0]
	v_fma_mix_f32 v70, v116, v226, v70 op_sel:[0,1,0] op_sel_hi:[0,1,0]
	v_fma_mix_f32 v71, v116, v238, v71 op_sel:[0,1,0] op_sel_hi:[0,1,0]
	v_fma_mix_f32 v73, v107, v203, v73 op_sel_hi:[0,1,0]
	v_fma_mix_f32 v69, v107, v213, v69 op_sel_hi:[0,1,0]
	v_fma_mix_f32 v70, v107, v221, v70 op_sel_hi:[0,1,0]
	v_fma_mix_f32 v71, v107, v235, v71 op_sel_hi:[0,1,0]
	v_fma_mix_f32 v73, v117, v209, v73 op_sel_hi:[0,1,0]
	v_fma_mix_f32 v69, v117, v217, v69 op_sel_hi:[0,1,0]
	v_fma_mix_f32 v70, v117, v227, v70 op_sel_hi:[0,1,0]
	v_fma_mix_f32 v71, v117, v239, v71 op_sel_hi:[0,1,0]
	v_fma_mix_f32 v73, v108, v203, v73 op_sel:[0,1,0] op_sel_hi:[0,1,0]
	v_fma_mix_f32 v69, v108, v213, v69 op_sel:[0,1,0] op_sel_hi:[0,1,0]
	v_fma_mix_f32 v70, v108, v221, v70 op_sel:[0,1,0] op_sel_hi:[0,1,0]
	v_fma_mix_f32 v71, v108, v235, v71 op_sel:[0,1,0] op_sel_hi:[0,1,0]
	v_fma_mix_f32 v73, v118, v209, v73 op_sel:[0,1,0] op_sel_hi:[0,1,0]
	v_fma_mix_f32 v69, v118, v217, v69 op_sel:[0,1,0] op_sel_hi:[0,1,0]
	v_fma_mix_f32 v70, v118, v227, v70 op_sel:[0,1,0] op_sel_hi:[0,1,0]
	v_fma_mix_f32 v71, v118, v239, v71 op_sel:[0,1,0] op_sel_hi:[0,1,0]
	ds_read_b128 v[200:203], v240 offset:256
	ds_read_b128 v[206:209], v240 offset:272
	ds_read_b128 v[210:213], v240 offset:320
	ds_read_b128 v[214:217], v240 offset:336
	ds_read_b128 v[218:221], v240 offset:384
	ds_read_b128 v[224:227], v240 offset:400
	ds_read_b128 v[232:235], v240 offset:448
	ds_read_b128 v[236:239], v240 offset:464
	v_mul_f32_e64 v241, |v73|, s86
	v_mul_f32_e64 v242, |v69|, s86
	v_mul_f32_e64 v243, |v70|, s86
	v_mul_f32_e64 v244, |v71|, s86
	v_exp_f32_e32 v241, v241
	v_exp_f32_e32 v242, v242
	v_exp_f32_e32 v243, v243
	v_exp_f32_e32 v244, v244
	v_add_f32_e32 v241, 1.0, v241
	v_add_f32_e32 v242, 1.0, v242
	v_add_f32_e32 v243, 1.0, v243
	v_add_f32_e32 v244, 1.0, v244
	v_log_f32_e32 v241, v241
	v_log_f32_e32 v242, v242
	v_log_f32_e32 v243, v243
	v_log_f32_e32 v244, v244
	v_mul_f32_e32 v245, 0x3f317217, v241
	v_mul_f32_e32 v246, 0x3f317217, v242
	v_mul_f32_e32 v247, 0x3f317217, v243
	v_mul_f32_e32 v248, 0x3f317217, v244
	v_fma_f32 v245, v241, s73, -v245
	v_fma_f32 v246, v242, s73, -v246
	v_fma_f32 v247, v243, s73, -v247
	v_fma_f32 v248, v244, s73, -v248
	v_fmac_f32_e32 v245, 0x3377d1cf, v241
	v_fmac_f32_e32 v246, 0x3377d1cf, v242
	v_fmac_f32_e32 v247, 0x3377d1cf, v243
	v_fmac_f32_e32 v248, 0x3377d1cf, v244
	v_fmac_f32_e32 v245, 0x3f317217, v241
	v_fmac_f32_e32 v246, 0x3f317217, v242
	v_fmac_f32_e32 v247, 0x3f317217, v243
	v_fmac_f32_e32 v248, 0x3f317217, v244
	v_min_f32_e32 v73, 0, v73
	v_min_f32_e32 v69, 0, v69
	v_min_f32_e32 v70, 0, v70
	v_min_f32_e32 v71, 0, v71
	v_sub_f32_e32 v73, v73, v245
	v_sub_f32_e32 v69, v69, v246
	v_sub_f32_e32 v70, v70, v247
	v_sub_f32_e32 v71, v71, v248
	v_mul_f32_e32 v73, 0x3d800000, v73
	v_mul_f32_e32 v69, 0x3d800000, v69
	v_mul_f32_e32 v70, 0x3d800000, v70
	v_mul_f32_e32 v71, 0x3d800000, v71
	s_waitcnt lgkmcnt(0)
	v_fma_mix_f32 v74, v101, v200, v100 op_sel_hi:[0,1,0]
	v_fma_mix_f32 v75, v101, v210, v100 op_sel_hi:[0,1,0]
	v_fma_mix_f32 v76, v101, v218, v100 op_sel_hi:[0,1,0]
	v_fma_mix_f32 v77, v101, v232, v100 op_sel_hi:[0,1,0]
	v_fma_mix_f32 v74, v109, v206, v74 op_sel_hi:[0,1,0]
	v_fma_mix_f32 v75, v109, v214, v75 op_sel_hi:[0,1,0]
	v_fma_mix_f32 v76, v109, v224, v76 op_sel_hi:[0,1,0]
	v_fma_mix_f32 v77, v109, v236, v77 op_sel_hi:[0,1,0]
	v_fma_mix_f32 v74, v102, v200, v74 op_sel:[0,1,0] op_sel_hi:[0,1,0]
	v_fma_mix_f32 v75, v102, v210, v75 op_sel:[0,1,0] op_sel_hi:[0,1,0]
	v_fma_mix_f32 v76, v102, v218, v76 op_sel:[0,1,0] op_sel_hi:[0,1,0]
	v_fma_mix_f32 v77, v102, v232, v77 op_sel:[0,1,0] op_sel_hi:[0,1,0]
	v_fma_mix_f32 v74, v110, v206, v74 op_sel:[0,1,0] op_sel_hi:[0,1,0]
	v_fma_mix_f32 v75, v110, v214, v75 op_sel:[0,1,0] op_sel_hi:[0,1,0]
	v_fma_mix_f32 v76, v110, v224, v76 op_sel:[0,1,0] op_sel_hi:[0,1,0]
	v_fma_mix_f32 v77, v110, v236, v77 op_sel:[0,1,0] op_sel_hi:[0,1,0]
	v_fma_mix_f32 v74, v103, v201, v74 op_sel_hi:[0,1,0]
	v_fma_mix_f32 v75, v103, v211, v75 op_sel_hi:[0,1,0]
	v_fma_mix_f32 v76, v103, v219, v76 op_sel_hi:[0,1,0]
	v_fma_mix_f32 v77, v103, v233, v77 op_sel_hi:[0,1,0]
	v_fma_mix_f32 v74, v111, v207, v74 op_sel_hi:[0,1,0]
	v_fma_mix_f32 v75, v111, v215, v75 op_sel_hi:[0,1,0]
	v_fma_mix_f32 v76, v111, v225, v76 op_sel_hi:[0,1,0]
	v_fma_mix_f32 v77, v111, v237, v77 op_sel_hi:[0,1,0]
	v_fma_mix_f32 v74, v104, v201, v74 op_sel:[0,1,0] op_sel_hi:[0,1,0]
	v_fma_mix_f32 v75, v104, v211, v75 op_sel:[0,1,0] op_sel_hi:[0,1,0]
	v_fma_mix_f32 v76, v104, v219, v76 op_sel:[0,1,0] op_sel_hi:[0,1,0]
	v_fma_mix_f32 v77, v104, v233, v77 op_sel:[0,1,0] op_sel_hi:[0,1,0]
	v_fma_mix_f32 v74, v112, v207, v74 op_sel:[0,1,0] op_sel_hi:[0,1,0]
	v_fma_mix_f32 v75, v112, v215, v75 op_sel:[0,1,0] op_sel_hi:[0,1,0]
	v_fma_mix_f32 v76, v112, v225, v76 op_sel:[0,1,0] op_sel_hi:[0,1,0]
	v_fma_mix_f32 v77, v112, v237, v77 op_sel:[0,1,0] op_sel_hi:[0,1,0]
	v_fma_mix_f32 v74, v105, v202, v74 op_sel_hi:[0,1,0]
	v_fma_mix_f32 v75, v105, v212, v75 op_sel_hi:[0,1,0]
	v_fma_mix_f32 v76, v105, v220, v76 op_sel_hi:[0,1,0]
	v_fma_mix_f32 v77, v105, v234, v77 op_sel_hi:[0,1,0]
	v_fma_mix_f32 v74, v114, v208, v74 op_sel_hi:[0,1,0]
	v_fma_mix_f32 v75, v114, v216, v75 op_sel_hi:[0,1,0]
	v_fma_mix_f32 v76, v114, v226, v76 op_sel_hi:[0,1,0]
	v_fma_mix_f32 v77, v114, v238, v77 op_sel_hi:[0,1,0]
	v_fma_mix_f32 v74, v106, v202, v74 op_sel:[0,1,0] op_sel_hi:[0,1,0]
	v_fma_mix_f32 v75, v106, v212, v75 op_sel:[0,1,0] op_sel_hi:[0,1,0]
	v_fma_mix_f32 v76, v106, v220, v76 op_sel:[0,1,0] op_sel_hi:[0,1,0]
	v_fma_mix_f32 v77, v106, v234, v77 op_sel:[0,1,0] op_sel_hi:[0,1,0]
	v_fma_mix_f32 v74, v116, v208, v74 op_sel:[0,1,0] op_sel_hi:[0,1,0]
	v_fma_mix_f32 v75, v116, v216, v75 op_sel:[0,1,0] op_sel_hi:[0,1,0]
	v_fma_mix_f32 v76, v116, v226, v76 op_sel:[0,1,0] op_sel_hi:[0,1,0]
	v_fma_mix_f32 v77, v116, v238, v77 op_sel:[0,1,0] op_sel_hi:[0,1,0]
	v_fma_mix_f32 v74, v107, v203, v74 op_sel_hi:[0,1,0]
	v_fma_mix_f32 v75, v107, v213, v75 op_sel_hi:[0,1,0]
	v_fma_mix_f32 v76, v107, v221, v76 op_sel_hi:[0,1,0]
	v_fma_mix_f32 v77, v107, v235, v77 op_sel_hi:[0,1,0]
	v_fma_mix_f32 v74, v117, v209, v74 op_sel_hi:[0,1,0]
	v_fma_mix_f32 v75, v117, v217, v75 op_sel_hi:[0,1,0]
	v_fma_mix_f32 v76, v117, v227, v76 op_sel_hi:[0,1,0]
	v_fma_mix_f32 v77, v117, v239, v77 op_sel_hi:[0,1,0]
	v_fma_mix_f32 v74, v108, v203, v74 op_sel:[0,1,0] op_sel_hi:[0,1,0]
	v_fma_mix_f32 v75, v108, v213, v75 op_sel:[0,1,0] op_sel_hi:[0,1,0]
	v_fma_mix_f32 v76, v108, v221, v76 op_sel:[0,1,0] op_sel_hi:[0,1,0]
	v_fma_mix_f32 v77, v108, v235, v77 op_sel:[0,1,0] op_sel_hi:[0,1,0]
	v_fma_mix_f32 v74, v118, v209, v74 op_sel:[0,1,0] op_sel_hi:[0,1,0]
	v_fma_mix_f32 v75, v118, v217, v75 op_sel:[0,1,0] op_sel_hi:[0,1,0]
	v_fma_mix_f32 v76, v118, v227, v76 op_sel:[0,1,0] op_sel_hi:[0,1,0]
	v_fma_mix_f32 v77, v118, v239, v77 op_sel:[0,1,0] op_sel_hi:[0,1,0]
	ds_read_b128 v[200:203], v240 offset:512
	ds_read_b128 v[206:209], v240 offset:528
	ds_read_b128 v[210:213], v240 offset:576
	ds_read_b128 v[214:217], v240 offset:592
	ds_read_b128 v[218:221], v240 offset:640
	ds_read_b128 v[224:227], v240 offset:656
	ds_read_b128 v[232:235], v240 offset:704
	ds_read_b128 v[236:239], v240 offset:720
	v_mul_f32_e64 v241, |v74|, s86
	v_mul_f32_e64 v242, |v75|, s86
	v_mul_f32_e64 v243, |v76|, s86
	v_mul_f32_e64 v244, |v77|, s86
	v_exp_f32_e32 v241, v241
	v_exp_f32_e32 v242, v242
	v_exp_f32_e32 v243, v243
	v_exp_f32_e32 v244, v244
	v_add_f32_e32 v241, 1.0, v241
	v_add_f32_e32 v242, 1.0, v242
	v_add_f32_e32 v243, 1.0, v243
	v_add_f32_e32 v244, 1.0, v244
	v_log_f32_e32 v241, v241
	v_log_f32_e32 v242, v242
	v_log_f32_e32 v243, v243
	v_log_f32_e32 v244, v244
	v_mul_f32_e32 v245, 0x3f317217, v241
	v_mul_f32_e32 v246, 0x3f317217, v242
	v_mul_f32_e32 v247, 0x3f317217, v243
	v_mul_f32_e32 v248, 0x3f317217, v244
	v_fma_f32 v245, v241, s73, -v245
	v_fma_f32 v246, v242, s73, -v246
	v_fma_f32 v247, v243, s73, -v247
	v_fma_f32 v248, v244, s73, -v248
	v_fmac_f32_e32 v245, 0x3377d1cf, v241
	v_fmac_f32_e32 v246, 0x3377d1cf, v242
	v_fmac_f32_e32 v247, 0x3377d1cf, v243
	v_fmac_f32_e32 v248, 0x3377d1cf, v244
	v_fmac_f32_e32 v245, 0x3f317217, v241
	v_fmac_f32_e32 v246, 0x3f317217, v242
	v_fmac_f32_e32 v247, 0x3f317217, v243
	v_fmac_f32_e32 v248, 0x3f317217, v244
	v_min_f32_e32 v74, 0, v74
	v_min_f32_e32 v75, 0, v75
	v_min_f32_e32 v76, 0, v76
	v_min_f32_e32 v77, 0, v77
	v_sub_f32_e32 v74, v74, v245
	v_sub_f32_e32 v75, v75, v246
	v_sub_f32_e32 v76, v76, v247
	v_sub_f32_e32 v77, v77, v248
	v_mul_f32_e32 v74, 0x3d800000, v74
	v_mul_f32_e32 v75, 0x3d800000, v75
	v_mul_f32_e32 v76, 0x3d800000, v76
	v_mul_f32_e32 v77, 0x3d800000, v77
	s_waitcnt lgkmcnt(0)
	v_fma_mix_f32 v78, v101, v200, v100 op_sel_hi:[0,1,0]
	v_fma_mix_f32 v79, v101, v210, v100 op_sel_hi:[0,1,0]
	v_fma_mix_f32 v80, v101, v218, v100 op_sel_hi:[0,1,0]
	v_fma_mix_f32 v81, v101, v232, v100 op_sel_hi:[0,1,0]
	v_fma_mix_f32 v78, v109, v206, v78 op_sel_hi:[0,1,0]
	v_fma_mix_f32 v79, v109, v214, v79 op_sel_hi:[0,1,0]
	v_fma_mix_f32 v80, v109, v224, v80 op_sel_hi:[0,1,0]
	v_fma_mix_f32 v81, v109, v236, v81 op_sel_hi:[0,1,0]
	v_fma_mix_f32 v78, v102, v200, v78 op_sel:[0,1,0] op_sel_hi:[0,1,0]
	v_fma_mix_f32 v79, v102, v210, v79 op_sel:[0,1,0] op_sel_hi:[0,1,0]
	v_fma_mix_f32 v80, v102, v218, v80 op_sel:[0,1,0] op_sel_hi:[0,1,0]
	v_fma_mix_f32 v81, v102, v232, v81 op_sel:[0,1,0] op_sel_hi:[0,1,0]
	v_fma_mix_f32 v78, v110, v206, v78 op_sel:[0,1,0] op_sel_hi:[0,1,0]
	v_fma_mix_f32 v79, v110, v214, v79 op_sel:[0,1,0] op_sel_hi:[0,1,0]
	v_fma_mix_f32 v80, v110, v224, v80 op_sel:[0,1,0] op_sel_hi:[0,1,0]
	v_fma_mix_f32 v81, v110, v236, v81 op_sel:[0,1,0] op_sel_hi:[0,1,0]
	v_fma_mix_f32 v78, v103, v201, v78 op_sel_hi:[0,1,0]
	v_fma_mix_f32 v79, v103, v211, v79 op_sel_hi:[0,1,0]
	v_fma_mix_f32 v80, v103, v219, v80 op_sel_hi:[0,1,0]
	v_fma_mix_f32 v81, v103, v233, v81 op_sel_hi:[0,1,0]
	v_fma_mix_f32 v78, v111, v207, v78 op_sel_hi:[0,1,0]
	v_fma_mix_f32 v79, v111, v215, v79 op_sel_hi:[0,1,0]
	v_fma_mix_f32 v80, v111, v225, v80 op_sel_hi:[0,1,0]
	v_fma_mix_f32 v81, v111, v237, v81 op_sel_hi:[0,1,0]
	v_fma_mix_f32 v78, v104, v201, v78 op_sel:[0,1,0] op_sel_hi:[0,1,0]
	v_fma_mix_f32 v79, v104, v211, v79 op_sel:[0,1,0] op_sel_hi:[0,1,0]
	v_fma_mix_f32 v80, v104, v219, v80 op_sel:[0,1,0] op_sel_hi:[0,1,0]
	v_fma_mix_f32 v81, v104, v233, v81 op_sel:[0,1,0] op_sel_hi:[0,1,0]
	v_fma_mix_f32 v78, v112, v207, v78 op_sel:[0,1,0] op_sel_hi:[0,1,0]
	v_fma_mix_f32 v79, v112, v215, v79 op_sel:[0,1,0] op_sel_hi:[0,1,0]
	v_fma_mix_f32 v80, v112, v225, v80 op_sel:[0,1,0] op_sel_hi:[0,1,0]
	v_fma_mix_f32 v81, v112, v237, v81 op_sel:[0,1,0] op_sel_hi:[0,1,0]
	v_fma_mix_f32 v78, v105, v202, v78 op_sel_hi:[0,1,0]
	v_fma_mix_f32 v79, v105, v212, v79 op_sel_hi:[0,1,0]
	v_fma_mix_f32 v80, v105, v220, v80 op_sel_hi:[0,1,0]
	v_fma_mix_f32 v81, v105, v234, v81 op_sel_hi:[0,1,0]
	v_fma_mix_f32 v78, v114, v208, v78 op_sel_hi:[0,1,0]
	v_fma_mix_f32 v79, v114, v216, v79 op_sel_hi:[0,1,0]
	v_fma_mix_f32 v80, v114, v226, v80 op_sel_hi:[0,1,0]
	v_fma_mix_f32 v81, v114, v238, v81 op_sel_hi:[0,1,0]
	v_fma_mix_f32 v78, v106, v202, v78 op_sel:[0,1,0] op_sel_hi:[0,1,0]
	v_fma_mix_f32 v79, v106, v212, v79 op_sel:[0,1,0] op_sel_hi:[0,1,0]
	v_fma_mix_f32 v80, v106, v220, v80 op_sel:[0,1,0] op_sel_hi:[0,1,0]
	v_fma_mix_f32 v81, v106, v234, v81 op_sel:[0,1,0] op_sel_hi:[0,1,0]
	v_fma_mix_f32 v78, v116, v208, v78 op_sel:[0,1,0] op_sel_hi:[0,1,0]
	v_fma_mix_f32 v79, v116, v216, v79 op_sel:[0,1,0] op_sel_hi:[0,1,0]
	v_fma_mix_f32 v80, v116, v226, v80 op_sel:[0,1,0] op_sel_hi:[0,1,0]
	v_fma_mix_f32 v81, v116, v238, v81 op_sel:[0,1,0] op_sel_hi:[0,1,0]
	v_fma_mix_f32 v78, v107, v203, v78 op_sel_hi:[0,1,0]
	v_fma_mix_f32 v79, v107, v213, v79 op_sel_hi:[0,1,0]
	v_fma_mix_f32 v80, v107, v221, v80 op_sel_hi:[0,1,0]
	v_fma_mix_f32 v81, v107, v235, v81 op_sel_hi:[0,1,0]
	v_fma_mix_f32 v78, v117, v209, v78 op_sel_hi:[0,1,0]
	v_fma_mix_f32 v79, v117, v217, v79 op_sel_hi:[0,1,0]
	v_fma_mix_f32 v80, v117, v227, v80 op_sel_hi:[0,1,0]
	v_fma_mix_f32 v81, v117, v239, v81 op_sel_hi:[0,1,0]
	v_fma_mix_f32 v78, v108, v203, v78 op_sel:[0,1,0] op_sel_hi:[0,1,0]
	v_fma_mix_f32 v79, v108, v213, v79 op_sel:[0,1,0] op_sel_hi:[0,1,0]
	v_fma_mix_f32 v80, v108, v221, v80 op_sel:[0,1,0] op_sel_hi:[0,1,0]
	v_fma_mix_f32 v81, v108, v235, v81 op_sel:[0,1,0] op_sel_hi:[0,1,0]
	v_fma_mix_f32 v78, v118, v209, v78 op_sel:[0,1,0] op_sel_hi:[0,1,0]
	v_fma_mix_f32 v79, v118, v217, v79 op_sel:[0,1,0] op_sel_hi:[0,1,0]
	v_fma_mix_f32 v80, v118, v227, v80 op_sel:[0,1,0] op_sel_hi:[0,1,0]
	v_fma_mix_f32 v81, v118, v239, v81 op_sel:[0,1,0] op_sel_hi:[0,1,0]
	ds_read_b128 v[200:203], v240 offset:768
	ds_read_b128 v[206:209], v240 offset:784
	ds_read_b128 v[210:213], v240 offset:832
	ds_read_b128 v[214:217], v240 offset:848
	ds_read_b128 v[218:221], v240 offset:896
	ds_read_b128 v[224:227], v240 offset:912
	ds_read_b128 v[232:235], v240 offset:960
	ds_read_b128 v[236:239], v240 offset:976
	v_mul_f32_e64 v241, |v78|, s86
	v_mul_f32_e64 v242, |v79|, s86
	v_mul_f32_e64 v243, |v80|, s86
	v_mul_f32_e64 v244, |v81|, s86
	v_exp_f32_e32 v241, v241
	v_exp_f32_e32 v242, v242
	v_exp_f32_e32 v243, v243
	v_exp_f32_e32 v244, v244
	v_add_f32_e32 v241, 1.0, v241
	v_add_f32_e32 v242, 1.0, v242
	v_add_f32_e32 v243, 1.0, v243
	v_add_f32_e32 v244, 1.0, v244
	v_log_f32_e32 v241, v241
	v_log_f32_e32 v242, v242
	v_log_f32_e32 v243, v243
	v_log_f32_e32 v244, v244
	v_mul_f32_e32 v245, 0x3f317217, v241
	v_mul_f32_e32 v246, 0x3f317217, v242
	v_mul_f32_e32 v247, 0x3f317217, v243
	v_mul_f32_e32 v248, 0x3f317217, v244
	v_fma_f32 v245, v241, s73, -v245
	v_fma_f32 v246, v242, s73, -v246
	v_fma_f32 v247, v243, s73, -v247
	v_fma_f32 v248, v244, s73, -v248
	v_fmac_f32_e32 v245, 0x3377d1cf, v241
	v_fmac_f32_e32 v246, 0x3377d1cf, v242
	v_fmac_f32_e32 v247, 0x3377d1cf, v243
	v_fmac_f32_e32 v248, 0x3377d1cf, v244
	v_fmac_f32_e32 v245, 0x3f317217, v241
	v_fmac_f32_e32 v246, 0x3f317217, v242
	v_fmac_f32_e32 v247, 0x3f317217, v243
	v_fmac_f32_e32 v248, 0x3f317217, v244
	v_min_f32_e32 v78, 0, v78
	v_min_f32_e32 v79, 0, v79
	v_min_f32_e32 v80, 0, v80
	v_min_f32_e32 v81, 0, v81
	v_sub_f32_e32 v78, v78, v245
	v_sub_f32_e32 v79, v79, v246
	v_sub_f32_e32 v80, v80, v247
	v_sub_f32_e32 v81, v81, v248
	v_mul_f32_e32 v78, 0x3d800000, v78
	v_mul_f32_e32 v79, 0x3d800000, v79
	v_mul_f32_e32 v80, 0x3d800000, v80
	v_mul_f32_e32 v81, 0x3d800000, v81
	s_waitcnt lgkmcnt(0)
	v_fma_mix_f32 v82, v101, v200, v100 op_sel_hi:[0,1,0]
	v_fma_mix_f32 v84, v101, v210, v100 op_sel_hi:[0,1,0]
	v_fma_mix_f32 v68, v101, v218, v100 op_sel_hi:[0,1,0]
	v_fma_mix_f32 v83, v101, v232, v100 op_sel_hi:[0,1,0]
	v_fma_mix_f32 v82, v109, v206, v82 op_sel_hi:[0,1,0]
	v_fma_mix_f32 v84, v109, v214, v84 op_sel_hi:[0,1,0]
	v_fma_mix_f32 v68, v109, v224, v68 op_sel_hi:[0,1,0]
	v_fma_mix_f32 v83, v109, v236, v83 op_sel_hi:[0,1,0]
	v_fma_mix_f32 v82, v102, v200, v82 op_sel:[0,1,0] op_sel_hi:[0,1,0]
	v_fma_mix_f32 v84, v102, v210, v84 op_sel:[0,1,0] op_sel_hi:[0,1,0]
	v_fma_mix_f32 v68, v102, v218, v68 op_sel:[0,1,0] op_sel_hi:[0,1,0]
	v_fma_mix_f32 v83, v102, v232, v83 op_sel:[0,1,0] op_sel_hi:[0,1,0]
	v_fma_mix_f32 v82, v110, v206, v82 op_sel:[0,1,0] op_sel_hi:[0,1,0]
	v_fma_mix_f32 v84, v110, v214, v84 op_sel:[0,1,0] op_sel_hi:[0,1,0]
	v_fma_mix_f32 v68, v110, v224, v68 op_sel:[0,1,0] op_sel_hi:[0,1,0]
	v_fma_mix_f32 v83, v110, v236, v83 op_sel:[0,1,0] op_sel_hi:[0,1,0]
	v_fma_mix_f32 v82, v103, v201, v82 op_sel_hi:[0,1,0]
	v_fma_mix_f32 v84, v103, v211, v84 op_sel_hi:[0,1,0]
	v_fma_mix_f32 v68, v103, v219, v68 op_sel_hi:[0,1,0]
	v_fma_mix_f32 v83, v103, v233, v83 op_sel_hi:[0,1,0]
	v_fma_mix_f32 v82, v111, v207, v82 op_sel_hi:[0,1,0]
	v_fma_mix_f32 v84, v111, v215, v84 op_sel_hi:[0,1,0]
	v_fma_mix_f32 v68, v111, v225, v68 op_sel_hi:[0,1,0]
	v_fma_mix_f32 v83, v111, v237, v83 op_sel_hi:[0,1,0]
	v_fma_mix_f32 v82, v104, v201, v82 op_sel:[0,1,0] op_sel_hi:[0,1,0]
	v_fma_mix_f32 v84, v104, v211, v84 op_sel:[0,1,0] op_sel_hi:[0,1,0]
	v_fma_mix_f32 v68, v104, v219, v68 op_sel:[0,1,0] op_sel_hi:[0,1,0]
	v_fma_mix_f32 v83, v104, v233, v83 op_sel:[0,1,0] op_sel_hi:[0,1,0]
	v_fma_mix_f32 v82, v112, v207, v82 op_sel:[0,1,0] op_sel_hi:[0,1,0]
	v_fma_mix_f32 v84, v112, v215, v84 op_sel:[0,1,0] op_sel_hi:[0,1,0]
	v_fma_mix_f32 v68, v112, v225, v68 op_sel:[0,1,0] op_sel_hi:[0,1,0]
	v_fma_mix_f32 v83, v112, v237, v83 op_sel:[0,1,0] op_sel_hi:[0,1,0]
	v_fma_mix_f32 v82, v105, v202, v82 op_sel_hi:[0,1,0]
	v_fma_mix_f32 v84, v105, v212, v84 op_sel_hi:[0,1,0]
	v_fma_mix_f32 v68, v105, v220, v68 op_sel_hi:[0,1,0]
	v_fma_mix_f32 v83, v105, v234, v83 op_sel_hi:[0,1,0]
	v_fma_mix_f32 v82, v114, v208, v82 op_sel_hi:[0,1,0]
	v_fma_mix_f32 v84, v114, v216, v84 op_sel_hi:[0,1,0]
	v_fma_mix_f32 v68, v114, v226, v68 op_sel_hi:[0,1,0]
	v_fma_mix_f32 v83, v114, v238, v83 op_sel_hi:[0,1,0]
	v_fma_mix_f32 v82, v106, v202, v82 op_sel:[0,1,0] op_sel_hi:[0,1,0]
	v_fma_mix_f32 v84, v106, v212, v84 op_sel:[0,1,0] op_sel_hi:[0,1,0]
	v_fma_mix_f32 v68, v106, v220, v68 op_sel:[0,1,0] op_sel_hi:[0,1,0]
	v_fma_mix_f32 v83, v106, v234, v83 op_sel:[0,1,0] op_sel_hi:[0,1,0]
	v_fma_mix_f32 v82, v116, v208, v82 op_sel:[0,1,0] op_sel_hi:[0,1,0]
	v_fma_mix_f32 v84, v116, v216, v84 op_sel:[0,1,0] op_sel_hi:[0,1,0]
	v_fma_mix_f32 v68, v116, v226, v68 op_sel:[0,1,0] op_sel_hi:[0,1,0]
	v_fma_mix_f32 v83, v116, v238, v83 op_sel:[0,1,0] op_sel_hi:[0,1,0]
	v_fma_mix_f32 v82, v107, v203, v82 op_sel_hi:[0,1,0]
	v_fma_mix_f32 v84, v107, v213, v84 op_sel_hi:[0,1,0]
	v_fma_mix_f32 v68, v107, v221, v68 op_sel_hi:[0,1,0]
	v_fma_mix_f32 v83, v107, v235, v83 op_sel_hi:[0,1,0]
	v_fma_mix_f32 v82, v117, v209, v82 op_sel_hi:[0,1,0]
	v_fma_mix_f32 v84, v117, v217, v84 op_sel_hi:[0,1,0]
	v_fma_mix_f32 v68, v117, v227, v68 op_sel_hi:[0,1,0]
	v_fma_mix_f32 v83, v117, v239, v83 op_sel_hi:[0,1,0]
	v_fma_mix_f32 v82, v108, v203, v82 op_sel:[0,1,0] op_sel_hi:[0,1,0]
	v_fma_mix_f32 v84, v108, v213, v84 op_sel:[0,1,0] op_sel_hi:[0,1,0]
	v_fma_mix_f32 v68, v108, v221, v68 op_sel:[0,1,0] op_sel_hi:[0,1,0]
	v_fma_mix_f32 v83, v108, v235, v83 op_sel:[0,1,0] op_sel_hi:[0,1,0]
	v_fma_mix_f32 v82, v118, v209, v82 op_sel:[0,1,0] op_sel_hi:[0,1,0]
	v_fma_mix_f32 v84, v118, v217, v84 op_sel:[0,1,0] op_sel_hi:[0,1,0]
	v_fma_mix_f32 v68, v118, v227, v68 op_sel:[0,1,0] op_sel_hi:[0,1,0]
	v_fma_mix_f32 v83, v118, v239, v83 op_sel:[0,1,0] op_sel_hi:[0,1,0]
	v_mul_f32_e64 v241, |v82|, s86
	v_mul_f32_e64 v242, |v84|, s86
	v_mul_f32_e64 v243, |v68|, s86
	v_mul_f32_e64 v244, |v83|, s86
	v_exp_f32_e32 v241, v241
	v_exp_f32_e32 v242, v242
	v_exp_f32_e32 v243, v243
	v_exp_f32_e32 v244, v244
	v_add_f32_e32 v241, 1.0, v241
	v_add_f32_e32 v242, 1.0, v242
	v_add_f32_e32 v243, 1.0, v243
	v_add_f32_e32 v244, 1.0, v244
	v_log_f32_e32 v241, v241
	v_log_f32_e32 v242, v242
	v_log_f32_e32 v243, v243
	v_log_f32_e32 v244, v244
	v_mul_f32_e32 v245, 0x3f317217, v241
	v_mul_f32_e32 v246, 0x3f317217, v242
	v_mul_f32_e32 v247, 0x3f317217, v243
	v_mul_f32_e32 v248, 0x3f317217, v244
	v_fma_f32 v245, v241, s73, -v245
	v_fma_f32 v246, v242, s73, -v246
	v_fma_f32 v247, v243, s73, -v247
	v_fma_f32 v248, v244, s73, -v248
	v_fmac_f32_e32 v245, 0x3377d1cf, v241
	v_fmac_f32_e32 v246, 0x3377d1cf, v242
	v_fmac_f32_e32 v247, 0x3377d1cf, v243
	v_fmac_f32_e32 v248, 0x3377d1cf, v244
	v_fmac_f32_e32 v245, 0x3f317217, v241
	v_fmac_f32_e32 v246, 0x3f317217, v242
	v_fmac_f32_e32 v247, 0x3f317217, v243
	v_fmac_f32_e32 v248, 0x3f317217, v244
	v_min_f32_e32 v82, 0, v82
	v_min_f32_e32 v84, 0, v84
	v_min_f32_e32 v68, 0, v68
	v_min_f32_e32 v83, 0, v83
	v_sub_f32_e32 v82, v82, v245
	v_sub_f32_e32 v84, v84, v246
	v_sub_f32_e32 v68, v68, v247
	v_sub_f32_e32 v83, v83, v248
	v_mul_f32_e32 v82, 0x3d800000, v82
	v_mul_f32_e32 v84, 0x3d800000, v84
	v_mul_f32_e32 v68, 0x3d800000, v68
	v_mul_f32_e32 v83, 0x3d800000, v83
	s_andn2_b64 vcc, exec, s[50:51]
	s_cbranch_vccnz .LBB0_1205
	v_add_f32_e32 v85, v68, v83
	v_add_f32_e32 v86, v84, v85
	v_add_f32_e32 v87, v82, v86
	v_add_f32_e32 v88, v81, v87
	v_add_f32_e32 v89, v80, v88
	v_add_f32_e32 v90, v79, v89
	v_add_f32_e32 v91, v78, v90
	v_add_f32_e32 v92, v77, v91
	v_add_f32_e32 v93, v76, v92
	v_add_f32_e32 v94, v75, v93
	v_add_f32_e32 v95, v74, v94
	v_add_f32_e32 v120, v71, v95
	v_add_f32_e32 v121, v70, v120
	v_add_f32_e32 v122, v69, v121
	v_add_f32_e32 v123, v73, v122
	s_mov_b64 s[16:17], 0

.LBB0_1563:
	s_or_b64 exec, exec, s[14:15]
	v_mov_b32_e32 v100, v2
	s_mov_b64 s[16:17], -1
	v_and_b32_e32 v101, 3, v100
	v_lshrrev_b32_e32 v102, 6, v100
	v_and_or_b32 v101, v102, s61, v101
	v_mul_lo_u32 v101, v101, s2
	v_lshrrev_b32_e32 v100, 1, v100
	v_add_u32_e32 v101, 0, v101
	v_and_b32_e32 v102, 0x60, v100
	v_and_b32_e32 v100, 30, v100
	v_add3_u32 v100, v101, v102, v100
	ds_write_b16 v100, v96 offset:35840
	ds_write_b16_d16_hi v100, v96 offset:35984
	ds_write_b16 v100, v97 offset:36128
	ds_write_b16_d16_hi v100, v97 offset:36272
	ds_write_b16 v100, v98 offset:36416
	ds_write_b16_d16_hi v100, v98 offset:36560
	ds_write_b16 v100, v99 offset:36704
	ds_write_b16_d16_hi v100, v99 offset:36848
	v_mov_b32_e32 v96, v2
	s_nop 0
	v_add_u32_e32 v97, 0x200, v96
	v_and_b32_e32 v98, 3, v96
	v_lshrrev_b32_e32 v97, 6, v97
	v_and_or_b32 v97, v97, s61, v98
	v_mul_lo_u32 v97, v97, s2
	v_lshrrev_b32_e32 v96, 1, v96
	v_add_u32_e32 v97, 0, v97
	v_and_b32_e32 v98, 0x60, v96
	v_and_b32_e32 v96, 30, v96
	v_add3_u32 v96, v97, v98, v96
	ds_write_b16 v96, v92 offset:35840
	ds_write_b16_d16_hi v96, v92 offset:35984
	ds_write_b16 v96, v93 offset:36128
	ds_write_b16_d16_hi v96, v93 offset:36272
	ds_write_b16 v96, v94 offset:36416
	ds_write_b16_d16_hi v96, v94 offset:36560
	ds_write_b16 v96, v95 offset:36704
	ds_write_b16_d16_hi v96, v95 offset:36848
	v_mov_b32_e32 v92, v2
	s_nop 0
	v_add_u32_e32 v93, 0x400, v92
	v_and_b32_e32 v94, 3, v92
	v_lshrrev_b32_e32 v93, 6, v93
	v_and_or_b32 v93, v93, s61, v94
	v_mul_lo_u32 v93, v93, s2
	v_lshrrev_b32_e32 v92, 1, v92
	v_add_u32_e32 v93, 0, v93
	v_and_b32_e32 v94, 0x60, v92
	v_and_b32_e32 v92, 30, v92
	v_add3_u32 v92, v93, v94, v92
	ds_write_b16 v92, v88 offset:35840
	ds_write_b16_d16_hi v92, v88 offset:35984
	ds_write_b16 v92, v89 offset:36128
	ds_write_b16_d16_hi v92, v89 offset:36272
	ds_write_b16 v92, v90 offset:36416
	ds_write_b16_d16_hi v92, v90 offset:36560
	ds_write_b16 v92, v91 offset:36704
	ds_write_b16_d16_hi v92, v91 offset:36848
	v_mov_b32_e32 v88, v2
	s_nop 0
	v_add_u32_e32 v89, 0x600, v88
	v_and_b32_e32 v90, 3, v88
	v_lshrrev_b32_e32 v89, 6, v89
	v_and_or_b32 v89, v89, s61, v90
	v_mul_lo_u32 v89, v89, s2
	v_lshrrev_b32_e32 v88, 1, v88
	v_add_u32_e32 v89, 0, v89
	v_and_b32_e32 v90, 0x60, v88
	v_and_b32_e32 v88, 30, v88
	v_add3_u32 v88, v89, v90, v88
	ds_write_b16 v88, v68 offset:35840
	ds_write_b16_d16_hi v88, v68 offset:35984
	ds_write_b16 v88, v69 offset:36128
	ds_write_b16_d16_hi v88, v69 offset:36272
	ds_write_b16 v88, v70 offset:36416
	ds_write_b16_d16_hi v88, v70 offset:36560
	ds_write_b16 v88, v71 offset:36704
	ds_write_b16_d16_hi v88, v71 offset:36848
	v_lshlrev_b32_e32 v68, 1, v104
	v_lshrrev_b32_e32 v70, 4, v2
	v_add_u32_e32 v2, 0x200, v2
	v_and_b32_e32 v68, 0xf0, v68
	v_lshrrev_b32_e32 v2, 4, v2
	v_add_u32_e32 v69, s3, v68
	v_add_u32_e32 v68, s65, v68
	v_mul_lo_u32 v70, v70, s72
	v_mul_lo_u32 v2, v2, s72
	v_add_u32_e32 v71, v69, v70
	v_add_u32_e32 v70, v68, v70
	v_add_u32_e32 v69, v69, v2
	v_add_u32_e32 v2, v68, v2
	ds_write_b128 v71, v[84:87]
	ds_write_b128 v70, v[76:79]
	ds_write_b128 v69, v[72:75]
	ds_write_b128 v2, v[80:83]
	v_mov_b32_e32 v72, v124
	v_mov_b32_e32 v2, v168
	s_waitcnt lgkmcnt(0)
	s_barrier
	s_nop 0
	v_lshl_add_u32 v240, v2, 10, s30
	ds_read_b128 v[200:203], v240
	ds_read_b128 v[206:209], v240 offset:16
	ds_read_b128 v[210:213], v240 offset:64
	ds_read_b128 v[214:217], v240 offset:80
	ds_read_b128 v[218:221], v240 offset:128
	ds_read_b128 v[224:227], v240 offset:144
	ds_read_b128 v[232:235], v240 offset:192
	ds_read_b128 v[236:239], v240 offset:208
	s_waitcnt lgkmcnt(0)
	v_fma_mix_f32 v73, v171, v200, v170 op_sel_hi:[0,1,0]
	v_fma_mix_f32 v69, v171, v210, v170 op_sel_hi:[0,1,0]
	v_fma_mix_f32 v70, v171, v218, v170 op_sel_hi:[0,1,0]
	v_fma_mix_f32 v71, v171, v232, v170 op_sel_hi:[0,1,0]
	v_fma_mix_f32 v73, v179, v206, v73 op_sel_hi:[0,1,0]
	v_fma_mix_f32 v69, v179, v214, v69 op_sel_hi:[0,1,0]
	v_fma_mix_f32 v70, v179, v224, v70 op_sel_hi:[0,1,0]
	v_fma_mix_f32 v71, v179, v236, v71 op_sel_hi:[0,1,0]
	v_fma_mix_f32 v73, v172, v200, v73 op_sel:[0,1,0] op_sel_hi:[0,1,0]
	v_fma_mix_f32 v69, v172, v210, v69 op_sel:[0,1,0] op_sel_hi:[0,1,0]
	v_fma_mix_f32 v70, v172, v218, v70 op_sel:[0,1,0] op_sel_hi:[0,1,0]
	v_fma_mix_f32 v71, v172, v232, v71 op_sel:[0,1,0] op_sel_hi:[0,1,0]
	v_fma_mix_f32 v73, v180, v206, v73 op_sel:[0,1,0] op_sel_hi:[0,1,0]
	v_fma_mix_f32 v69, v180, v214, v69 op_sel:[0,1,0] op_sel_hi:[0,1,0]
	v_fma_mix_f32 v70, v180, v224, v70 op_sel:[0,1,0] op_sel_hi:[0,1,0]
	v_fma_mix_f32 v71, v180, v236, v71 op_sel:[0,1,0] op_sel_hi:[0,1,0]
	v_fma_mix_f32 v73, v173, v201, v73 op_sel_hi:[0,1,0]
	v_fma_mix_f32 v69, v173, v211, v69 op_sel_hi:[0,1,0]
	v_fma_mix_f32 v70, v173, v219, v70 op_sel_hi:[0,1,0]
	v_fma_mix_f32 v71, v173, v233, v71 op_sel_hi:[0,1,0]
	v_fma_mix_f32 v73, v181, v207, v73 op_sel_hi:[0,1,0]
	v_fma_mix_f32 v69, v181, v215, v69 op_sel_hi:[0,1,0]
	v_fma_mix_f32 v70, v181, v225, v70 op_sel_hi:[0,1,0]
	v_fma_mix_f32 v71, v181, v237, v71 op_sel_hi:[0,1,0]
	v_fma_mix_f32 v73, v174, v201, v73 op_sel:[0,1,0] op_sel_hi:[0,1,0]
	v_fma_mix_f32 v69, v174, v211, v69 op_sel:[0,1,0] op_sel_hi:[0,1,0]
	v_fma_mix_f32 v70, v174, v219, v70 op_sel:[0,1,0] op_sel_hi:[0,1,0]
	v_fma_mix_f32 v71, v174, v233, v71 op_sel:[0,1,0] op_sel_hi:[0,1,0]
	v_fma_mix_f32 v73, v182, v207, v73 op_sel:[0,1,0] op_sel_hi:[0,1,0]
	v_fma_mix_f32 v69, v182, v215, v69 op_sel:[0,1,0] op_sel_hi:[0,1,0]
	v_fma_mix_f32 v70, v182, v225, v70 op_sel:[0,1,0] op_sel_hi:[0,1,0]
	v_fma_mix_f32 v71, v182, v237, v71 op_sel:[0,1,0] op_sel_hi:[0,1,0]
	v_fma_mix_f32 v73, v175, v202, v73 op_sel_hi:[0,1,0]
	v_fma_mix_f32 v69, v175, v212, v69 op_sel_hi:[0,1,0]
	v_fma_mix_f32 v70, v175, v220, v70 op_sel_hi:[0,1,0]
	v_fma_mix_f32 v71, v175, v234, v71 op_sel_hi:[0,1,0]
	v_fma_mix_f32 v73, v183, v208, v73 op_sel_hi:[0,1,0]
	v_fma_mix_f32 v69, v183, v216, v69 op_sel_hi:[0,1,0]
	v_fma_mix_f32 v70, v183, v226, v70 op_sel_hi:[0,1,0]
	v_fma_mix_f32 v71, v183, v238, v71 op_sel_hi:[0,1,0]
	v_fma_mix_f32 v73, v176, v202, v73 op_sel:[0,1,0] op_sel_hi:[0,1,0]
	v_fma_mix_f32 v69, v176, v212, v69 op_sel:[0,1,0] op_sel_hi:[0,1,0]
	v_fma_mix_f32 v70, v176, v220, v70 op_sel:[0,1,0] op_sel_hi:[0,1,0]
	v_fma_mix_f32 v71, v176, v234, v71 op_sel:[0,1,0] op_sel_hi:[0,1,0]
	v_fma_mix_f32 v73, v184, v208, v73 op_sel:[0,1,0] op_sel_hi:[0,1,0]
	v_fma_mix_f32 v69, v184, v216, v69 op_sel:[0,1,0] op_sel_hi:[0,1,0]
	v_fma_mix_f32 v70, v184, v226, v70 op_sel:[0,1,0] op_sel_hi:[0,1,0]
	v_fma_mix_f32 v71, v184, v238, v71 op_sel:[0,1,0] op_sel_hi:[0,1,0]
	v_fma_mix_f32 v73, v177, v203, v73 op_sel_hi:[0,1,0]
	v_fma_mix_f32 v69, v177, v213, v69 op_sel_hi:[0,1,0]
	v_fma_mix_f32 v70, v177, v221, v70 op_sel_hi:[0,1,0]
	v_fma_mix_f32 v71, v177, v235, v71 op_sel_hi:[0,1,0]
	v_fma_mix_f32 v73, v185, v209, v73 op_sel_hi:[0,1,0]
	v_fma_mix_f32 v69, v185, v217, v69 op_sel_hi:[0,1,0]
	v_fma_mix_f32 v70, v185, v227, v70 op_sel_hi:[0,1,0]
	v_fma_mix_f32 v71, v185, v239, v71 op_sel_hi:[0,1,0]
	v_fma_mix_f32 v73, v178, v203, v73 op_sel:[0,1,0] op_sel_hi:[0,1,0]
	v_fma_mix_f32 v69, v178, v213, v69 op_sel:[0,1,0] op_sel_hi:[0,1,0]
	v_fma_mix_f32 v70, v178, v221, v70 op_sel:[0,1,0] op_sel_hi:[0,1,0]
	v_fma_mix_f32 v71, v178, v235, v71 op_sel:[0,1,0] op_sel_hi:[0,1,0]
	v_fma_mix_f32 v73, v186, v209, v73 op_sel:[0,1,0] op_sel_hi:[0,1,0]
	v_fma_mix_f32 v69, v186, v217, v69 op_sel:[0,1,0] op_sel_hi:[0,1,0]
	v_fma_mix_f32 v70, v186, v227, v70 op_sel:[0,1,0] op_sel_hi:[0,1,0]
	v_fma_mix_f32 v71, v186, v239, v71 op_sel:[0,1,0] op_sel_hi:[0,1,0]
	ds_read_b128 v[200:203], v240 offset:256
	ds_read_b128 v[206:209], v240 offset:272
	ds_read_b128 v[210:213], v240 offset:320
	ds_read_b128 v[214:217], v240 offset:336
	ds_read_b128 v[218:221], v240 offset:384
	ds_read_b128 v[224:227], v240 offset:400
	ds_read_b128 v[232:235], v240 offset:448
	ds_read_b128 v[236:239], v240 offset:464
	v_mul_f32_e64 v241, |v73|, s86
	v_mul_f32_e64 v242, |v69|, s86
	v_mul_f32_e64 v243, |v70|, s86
	v_mul_f32_e64 v244, |v71|, s86
	v_exp_f32_e32 v241, v241
	v_exp_f32_e32 v242, v242
	v_exp_f32_e32 v243, v243
	v_exp_f32_e32 v244, v244
	v_add_f32_e32 v241, 1.0, v241
	v_add_f32_e32 v242, 1.0, v242
	v_add_f32_e32 v243, 1.0, v243
	v_add_f32_e32 v244, 1.0, v244
	v_log_f32_e32 v241, v241
	v_log_f32_e32 v242, v242
	v_log_f32_e32 v243, v243
	v_log_f32_e32 v244, v244
	v_mul_f32_e32 v245, 0x3f317217, v241
	v_mul_f32_e32 v246, 0x3f317217, v242
	v_mul_f32_e32 v247, 0x3f317217, v243
	v_mul_f32_e32 v248, 0x3f317217, v244
	v_fma_f32 v245, v241, s73, -v245
	v_fma_f32 v246, v242, s73, -v246
	v_fma_f32 v247, v243, s73, -v247
	v_fma_f32 v248, v244, s73, -v248
	v_fmac_f32_e32 v245, 0x3377d1cf, v241
	v_fmac_f32_e32 v246, 0x3377d1cf, v242
	v_fmac_f32_e32 v247, 0x3377d1cf, v243
	v_fmac_f32_e32 v248, 0x3377d1cf, v244
	v_fmac_f32_e32 v245, 0x3f317217, v241
	v_fmac_f32_e32 v246, 0x3f317217, v242
	v_fmac_f32_e32 v247, 0x3f317217, v243
	v_fmac_f32_e32 v248, 0x3f317217, v244
	v_min_f32_e32 v73, 0, v73
	v_min_f32_e32 v69, 0, v69
	v_min_f32_e32 v70, 0, v70
	v_min_f32_e32 v71, 0, v71
	v_sub_f32_e32 v73, v73, v245
	v_sub_f32_e32 v69, v69, v246
	v_sub_f32_e32 v70, v70, v247
	v_sub_f32_e32 v71, v71, v248
	v_mul_f32_e32 v73, 0x3d800000, v73
	v_mul_f32_e32 v69, 0x3d800000, v69
	v_mul_f32_e32 v70, 0x3d800000, v70
	v_mul_f32_e32 v71, 0x3d800000, v71
	s_waitcnt lgkmcnt(0)
	v_fma_mix_f32 v74, v171, v200, v170 op_sel_hi:[0,1,0]
	v_fma_mix_f32 v75, v171, v210, v170 op_sel_hi:[0,1,0]
	v_fma_mix_f32 v76, v171, v218, v170 op_sel_hi:[0,1,0]
	v_fma_mix_f32 v77, v171, v232, v170 op_sel_hi:[0,1,0]
	v_fma_mix_f32 v74, v179, v206, v74 op_sel_hi:[0,1,0]
	v_fma_mix_f32 v75, v179, v214, v75 op_sel_hi:[0,1,0]
	v_fma_mix_f32 v76, v179, v224, v76 op_sel_hi:[0,1,0]
	v_fma_mix_f32 v77, v179, v236, v77 op_sel_hi:[0,1,0]
	v_fma_mix_f32 v74, v172, v200, v74 op_sel:[0,1,0] op_sel_hi:[0,1,0]
	v_fma_mix_f32 v75, v172, v210, v75 op_sel:[0,1,0] op_sel_hi:[0,1,0]
	v_fma_mix_f32 v76, v172, v218, v76 op_sel:[0,1,0] op_sel_hi:[0,1,0]
	v_fma_mix_f32 v77, v172, v232, v77 op_sel:[0,1,0] op_sel_hi:[0,1,0]
	v_fma_mix_f32 v74, v180, v206, v74 op_sel:[0,1,0] op_sel_hi:[0,1,0]
	v_fma_mix_f32 v75, v180, v214, v75 op_sel:[0,1,0] op_sel_hi:[0,1,0]
	v_fma_mix_f32 v76, v180, v224, v76 op_sel:[0,1,0] op_sel_hi:[0,1,0]
	v_fma_mix_f32 v77, v180, v236, v77 op_sel:[0,1,0] op_sel_hi:[0,1,0]
	v_fma_mix_f32 v74, v173, v201, v74 op_sel_hi:[0,1,0]
	v_fma_mix_f32 v75, v173, v211, v75 op_sel_hi:[0,1,0]
	v_fma_mix_f32 v76, v173, v219, v76 op_sel_hi:[0,1,0]
	v_fma_mix_f32 v77, v173, v233, v77 op_sel_hi:[0,1,0]
	v_fma_mix_f32 v74, v181, v207, v74 op_sel_hi:[0,1,0]
	v_fma_mix_f32 v75, v181, v215, v75 op_sel_hi:[0,1,0]
	v_fma_mix_f32 v76, v181, v225, v76 op_sel_hi:[0,1,0]
	v_fma_mix_f32 v77, v181, v237, v77 op_sel_hi:[0,1,0]
	v_fma_mix_f32 v74, v174, v201, v74 op_sel:[0,1,0] op_sel_hi:[0,1,0]
	v_fma_mix_f32 v75, v174, v211, v75 op_sel:[0,1,0] op_sel_hi:[0,1,0]
	v_fma_mix_f32 v76, v174, v219, v76 op_sel:[0,1,0] op_sel_hi:[0,1,0]
	v_fma_mix_f32 v77, v174, v233, v77 op_sel:[0,1,0] op_sel_hi:[0,1,0]
	v_fma_mix_f32 v74, v182, v207, v74 op_sel:[0,1,0] op_sel_hi:[0,1,0]
	v_fma_mix_f32 v75, v182, v215, v75 op_sel:[0,1,0] op_sel_hi:[0,1,0]
	v_fma_mix_f32 v76, v182, v225, v76 op_sel:[0,1,0] op_sel_hi:[0,1,0]
	v_fma_mix_f32 v77, v182, v237, v77 op_sel:[0,1,0] op_sel_hi:[0,1,0]
	v_fma_mix_f32 v74, v175, v202, v74 op_sel_hi:[0,1,0]
	v_fma_mix_f32 v75, v175, v212, v75 op_sel_hi:[0,1,0]
	v_fma_mix_f32 v76, v175, v220, v76 op_sel_hi:[0,1,0]
	v_fma_mix_f32 v77, v175, v234, v77 op_sel_hi:[0,1,0]
	v_fma_mix_f32 v74, v183, v208, v74 op_sel_hi:[0,1,0]
	v_fma_mix_f32 v75, v183, v216, v75 op_sel_hi:[0,1,0]
	v_fma_mix_f32 v76, v183, v226, v76 op_sel_hi:[0,1,0]
	v_fma_mix_f32 v77, v183, v238, v77 op_sel_hi:[0,1,0]
	v_fma_mix_f32 v74, v176, v202, v74 op_sel:[0,1,0] op_sel_hi:[0,1,0]
	v_fma_mix_f32 v75, v176, v212, v75 op_sel:[0,1,0] op_sel_hi:[0,1,0]
	v_fma_mix_f32 v76, v176, v220, v76 op_sel:[0,1,0] op_sel_hi:[0,1,0]
	v_fma_mix_f32 v77, v176, v234, v77 op_sel:[0,1,0] op_sel_hi:[0,1,0]
	v_fma_mix_f32 v74, v184, v208, v74 op_sel:[0,1,0] op_sel_hi:[0,1,0]
	v_fma_mix_f32 v75, v184, v216, v75 op_sel:[0,1,0] op_sel_hi:[0,1,0]
	v_fma_mix_f32 v76, v184, v226, v76 op_sel:[0,1,0] op_sel_hi:[0,1,0]
	v_fma_mix_f32 v77, v184, v238, v77 op_sel:[0,1,0] op_sel_hi:[0,1,0]
	v_fma_mix_f32 v74, v177, v203, v74 op_sel_hi:[0,1,0]
	v_fma_mix_f32 v75, v177, v213, v75 op_sel_hi:[0,1,0]
	v_fma_mix_f32 v76, v177, v221, v76 op_sel_hi:[0,1,0]
	v_fma_mix_f32 v77, v177, v235, v77 op_sel_hi:[0,1,0]
	v_fma_mix_f32 v74, v185, v209, v74 op_sel_hi:[0,1,0]
	v_fma_mix_f32 v75, v185, v217, v75 op_sel_hi:[0,1,0]
	v_fma_mix_f32 v76, v185, v227, v76 op_sel_hi:[0,1,0]
	v_fma_mix_f32 v77, v185, v239, v77 op_sel_hi:[0,1,0]
	v_fma_mix_f32 v74, v178, v203, v74 op_sel:[0,1,0] op_sel_hi:[0,1,0]
	v_fma_mix_f32 v75, v178, v213, v75 op_sel:[0,1,0] op_sel_hi:[0,1,0]
	v_fma_mix_f32 v76, v178, v221, v76 op_sel:[0,1,0] op_sel_hi:[0,1,0]
	v_fma_mix_f32 v77, v178, v235, v77 op_sel:[0,1,0] op_sel_hi:[0,1,0]
	v_fma_mix_f32 v74, v186, v209, v74 op_sel:[0,1,0] op_sel_hi:[0,1,0]
	v_fma_mix_f32 v75, v186, v217, v75 op_sel:[0,1,0] op_sel_hi:[0,1,0]
	v_fma_mix_f32 v76, v186, v227, v76 op_sel:[0,1,0] op_sel_hi:[0,1,0]
	v_fma_mix_f32 v77, v186, v239, v77 op_sel:[0,1,0] op_sel_hi:[0,1,0]
	ds_read_b128 v[200:203], v240 offset:512
	ds_read_b128 v[206:209], v240 offset:528
	ds_read_b128 v[210:213], v240 offset:576
	ds_read_b128 v[214:217], v240 offset:592
	ds_read_b128 v[218:221], v240 offset:640
	ds_read_b128 v[224:227], v240 offset:656
	ds_read_b128 v[232:235], v240 offset:704
	ds_read_b128 v[236:239], v240 offset:720
	v_mul_f32_e64 v241, |v74|, s86
	v_mul_f32_e64 v242, |v75|, s86
	v_mul_f32_e64 v243, |v76|, s86
	v_mul_f32_e64 v244, |v77|, s86
	v_exp_f32_e32 v241, v241
	v_exp_f32_e32 v242, v242
	v_exp_f32_e32 v243, v243
	v_exp_f32_e32 v244, v244
	v_add_f32_e32 v241, 1.0, v241
	v_add_f32_e32 v242, 1.0, v242
	v_add_f32_e32 v243, 1.0, v243
	v_add_f32_e32 v244, 1.0, v244
	v_log_f32_e32 v241, v241
	v_log_f32_e32 v242, v242
	v_log_f32_e32 v243, v243
	v_log_f32_e32 v244, v244
	v_mul_f32_e32 v245, 0x3f317217, v241
	v_mul_f32_e32 v246, 0x3f317217, v242
	v_mul_f32_e32 v247, 0x3f317217, v243
	v_mul_f32_e32 v248, 0x3f317217, v244
	v_fma_f32 v245, v241, s73, -v245
	v_fma_f32 v246, v242, s73, -v246
	v_fma_f32 v247, v243, s73, -v247
	v_fma_f32 v248, v244, s73, -v248
	v_fmac_f32_e32 v245, 0x3377d1cf, v241
	v_fmac_f32_e32 v246, 0x3377d1cf, v242
	v_fmac_f32_e32 v247, 0x3377d1cf, v243
	v_fmac_f32_e32 v248, 0x3377d1cf, v244
	v_fmac_f32_e32 v245, 0x3f317217, v241
	v_fmac_f32_e32 v246, 0x3f317217, v242
	v_fmac_f32_e32 v247, 0x3f317217, v243
	v_fmac_f32_e32 v248, 0x3f317217, v244
	v_min_f32_e32 v74, 0, v74
	v_min_f32_e32 v75, 0, v75
	v_min_f32_e32 v76, 0, v76
	v_min_f32_e32 v77, 0, v77
	v_sub_f32_e32 v74, v74, v245
	v_sub_f32_e32 v75, v75, v246
	v_sub_f32_e32 v76, v76, v247
	v_sub_f32_e32 v77, v77, v248
	v_mul_f32_e32 v74, 0x3d800000, v74
	v_mul_f32_e32 v75, 0x3d800000, v75
	v_mul_f32_e32 v76, 0x3d800000, v76
	v_mul_f32_e32 v77, 0x3d800000, v77
	s_waitcnt lgkmcnt(0)
	v_fma_mix_f32 v78, v171, v200, v170 op_sel_hi:[0,1,0]
	v_fma_mix_f32 v79, v171, v210, v170 op_sel_hi:[0,1,0]
	v_fma_mix_f32 v80, v171, v218, v170 op_sel_hi:[0,1,0]
	v_fma_mix_f32 v81, v171, v232, v170 op_sel_hi:[0,1,0]
	v_fma_mix_f32 v78, v179, v206, v78 op_sel_hi:[0,1,0]
	v_fma_mix_f32 v79, v179, v214, v79 op_sel_hi:[0,1,0]
	v_fma_mix_f32 v80, v179, v224, v80 op_sel_hi:[0,1,0]
	v_fma_mix_f32 v81, v179, v236, v81 op_sel_hi:[0,1,0]
	v_fma_mix_f32 v78, v172, v200, v78 op_sel:[0,1,0] op_sel_hi:[0,1,0]
	v_fma_mix_f32 v79, v172, v210, v79 op_sel:[0,1,0] op_sel_hi:[0,1,0]
	v_fma_mix_f32 v80, v172, v218, v80 op_sel:[0,1,0] op_sel_hi:[0,1,0]
	v_fma_mix_f32 v81, v172, v232, v81 op_sel:[0,1,0] op_sel_hi:[0,1,0]
	v_fma_mix_f32 v78, v180, v206, v78 op_sel:[0,1,0] op_sel_hi:[0,1,0]
	v_fma_mix_f32 v79, v180, v214, v79 op_sel:[0,1,0] op_sel_hi:[0,1,0]
	v_fma_mix_f32 v80, v180, v224, v80 op_sel:[0,1,0] op_sel_hi:[0,1,0]
	v_fma_mix_f32 v81, v180, v236, v81 op_sel:[0,1,0] op_sel_hi:[0,1,0]
	v_fma_mix_f32 v78, v173, v201, v78 op_sel_hi:[0,1,0]
	v_fma_mix_f32 v79, v173, v211, v79 op_sel_hi:[0,1,0]
	v_fma_mix_f32 v80, v173, v219, v80 op_sel_hi:[0,1,0]
	v_fma_mix_f32 v81, v173, v233, v81 op_sel_hi:[0,1,0]
	v_fma_mix_f32 v78, v181, v207, v78 op_sel_hi:[0,1,0]
	v_fma_mix_f32 v79, v181, v215, v79 op_sel_hi:[0,1,0]
	v_fma_mix_f32 v80, v181, v225, v80 op_sel_hi:[0,1,0]
	v_fma_mix_f32 v81, v181, v237, v81 op_sel_hi:[0,1,0]
	v_fma_mix_f32 v78, v174, v201, v78 op_sel:[0,1,0] op_sel_hi:[0,1,0]
	v_fma_mix_f32 v79, v174, v211, v79 op_sel:[0,1,0] op_sel_hi:[0,1,0]
	v_fma_mix_f32 v80, v174, v219, v80 op_sel:[0,1,0] op_sel_hi:[0,1,0]
	v_fma_mix_f32 v81, v174, v233, v81 op_sel:[0,1,0] op_sel_hi:[0,1,0]
	v_fma_mix_f32 v78, v182, v207, v78 op_sel:[0,1,0] op_sel_hi:[0,1,0]
	v_fma_mix_f32 v79, v182, v215, v79 op_sel:[0,1,0] op_sel_hi:[0,1,0]
	v_fma_mix_f32 v80, v182, v225, v80 op_sel:[0,1,0] op_sel_hi:[0,1,0]
	v_fma_mix_f32 v81, v182, v237, v81 op_sel:[0,1,0] op_sel_hi:[0,1,0]
	v_fma_mix_f32 v78, v175, v202, v78 op_sel_hi:[0,1,0]
	v_fma_mix_f32 v79, v175, v212, v79 op_sel_hi:[0,1,0]
	v_fma_mix_f32 v80, v175, v220, v80 op_sel_hi:[0,1,0]
	v_fma_mix_f32 v81, v175, v234, v81 op_sel_hi:[0,1,0]
	v_fma_mix_f32 v78, v183, v208, v78 op_sel_hi:[0,1,0]
	v_fma_mix_f32 v79, v183, v216, v79 op_sel_hi:[0,1,0]
	v_fma_mix_f32 v80, v183, v226, v80 op_sel_hi:[0,1,0]
	v_fma_mix_f32 v81, v183, v238, v81 op_sel_hi:[0,1,0]
	v_fma_mix_f32 v78, v176, v202, v78 op_sel:[0,1,0] op_sel_hi:[0,1,0]
	v_fma_mix_f32 v79, v176, v212, v79 op_sel:[0,1,0] op_sel_hi:[0,1,0]
	v_fma_mix_f32 v80, v176, v220, v80 op_sel:[0,1,0] op_sel_hi:[0,1,0]
	v_fma_mix_f32 v81, v176, v234, v81 op_sel:[0,1,0] op_sel_hi:[0,1,0]
	v_fma_mix_f32 v78, v184, v208, v78 op_sel:[0,1,0] op_sel_hi:[0,1,0]
	v_fma_mix_f32 v79, v184, v216, v79 op_sel:[0,1,0] op_sel_hi:[0,1,0]
	v_fma_mix_f32 v80, v184, v226, v80 op_sel:[0,1,0] op_sel_hi:[0,1,0]
	v_fma_mix_f32 v81, v184, v238, v81 op_sel:[0,1,0] op_sel_hi:[0,1,0]
	v_fma_mix_f32 v78, v177, v203, v78 op_sel_hi:[0,1,0]
	v_fma_mix_f32 v79, v177, v213, v79 op_sel_hi:[0,1,0]
	v_fma_mix_f32 v80, v177, v221, v80 op_sel_hi:[0,1,0]
	v_fma_mix_f32 v81, v177, v235, v81 op_sel_hi:[0,1,0]
	v_fma_mix_f32 v78, v185, v209, v78 op_sel_hi:[0,1,0]
	v_fma_mix_f32 v79, v185, v217, v79 op_sel_hi:[0,1,0]
	v_fma_mix_f32 v80, v185, v227, v80 op_sel_hi:[0,1,0]
	v_fma_mix_f32 v81, v185, v239, v81 op_sel_hi:[0,1,0]
	v_fma_mix_f32 v78, v178, v203, v78 op_sel:[0,1,0] op_sel_hi:[0,1,0]
	v_fma_mix_f32 v79, v178, v213, v79 op_sel:[0,1,0] op_sel_hi:[0,1,0]
	v_fma_mix_f32 v80, v178, v221, v80 op_sel:[0,1,0] op_sel_hi:[0,1,0]
	v_fma_mix_f32 v81, v178, v235, v81 op_sel:[0,1,0] op_sel_hi:[0,1,0]
	v_fma_mix_f32 v78, v186, v209, v78 op_sel:[0,1,0] op_sel_hi:[0,1,0]
	v_fma_mix_f32 v79, v186, v217, v79 op_sel:[0,1,0] op_sel_hi:[0,1,0]
	v_fma_mix_f32 v80, v186, v227, v80 op_sel:[0,1,0] op_sel_hi:[0,1,0]
	v_fma_mix_f32 v81, v186, v239, v81 op_sel:[0,1,0] op_sel_hi:[0,1,0]
	ds_read_b128 v[200:203], v240 offset:768
	ds_read_b128 v[206:209], v240 offset:784
	ds_read_b128 v[210:213], v240 offset:832
	ds_read_b128 v[214:217], v240 offset:848
	ds_read_b128 v[218:221], v240 offset:896
	ds_read_b128 v[224:227], v240 offset:912
	ds_read_b128 v[232:235], v240 offset:960
	ds_read_b128 v[236:239], v240 offset:976
	v_mul_f32_e64 v241, |v78|, s86
	v_mul_f32_e64 v242, |v79|, s86
	v_mul_f32_e64 v243, |v80|, s86
	v_mul_f32_e64 v244, |v81|, s86
	v_exp_f32_e32 v241, v241
	v_exp_f32_e32 v242, v242
	v_exp_f32_e32 v243, v243
	v_exp_f32_e32 v244, v244
	v_add_f32_e32 v241, 1.0, v241
	v_add_f32_e32 v242, 1.0, v242
	v_add_f32_e32 v243, 1.0, v243
	v_add_f32_e32 v244, 1.0, v244
	v_log_f32_e32 v241, v241
	v_log_f32_e32 v242, v242
	v_log_f32_e32 v243, v243
	v_log_f32_e32 v244, v244
	v_mul_f32_e32 v245, 0x3f317217, v241
	v_mul_f32_e32 v246, 0x3f317217, v242
	v_mul_f32_e32 v247, 0x3f317217, v243
	v_mul_f32_e32 v248, 0x3f317217, v244
	v_fma_f32 v245, v241, s73, -v245
	v_fma_f32 v246, v242, s73, -v246
	v_fma_f32 v247, v243, s73, -v247
	v_fma_f32 v248, v244, s73, -v248
	v_fmac_f32_e32 v245, 0x3377d1cf, v241
	v_fmac_f32_e32 v246, 0x3377d1cf, v242
	v_fmac_f32_e32 v247, 0x3377d1cf, v243
	v_fmac_f32_e32 v248, 0x3377d1cf, v244
	v_fmac_f32_e32 v245, 0x3f317217, v241
	v_fmac_f32_e32 v246, 0x3f317217, v242
	v_fmac_f32_e32 v247, 0x3f317217, v243
	v_fmac_f32_e32 v248, 0x3f317217, v244
	v_min_f32_e32 v78, 0, v78
	v_min_f32_e32 v79, 0, v79
	v_min_f32_e32 v80, 0, v80
	v_min_f32_e32 v81, 0, v81
	v_sub_f32_e32 v78, v78, v245
	v_sub_f32_e32 v79, v79, v246
	v_sub_f32_e32 v80, v80, v247
	v_sub_f32_e32 v81, v81, v248
	v_mul_f32_e32 v78, 0x3d800000, v78
	v_mul_f32_e32 v79, 0x3d800000, v79
	v_mul_f32_e32 v80, 0x3d800000, v80
	v_mul_f32_e32 v81, 0x3d800000, v81
	s_waitcnt lgkmcnt(0)
	v_fma_mix_f32 v84, v171, v200, v170 op_sel_hi:[0,1,0]
	v_fma_mix_f32 v85, v171, v210, v170 op_sel_hi:[0,1,0]
	v_fma_mix_f32 v68, v171, v218, v170 op_sel_hi:[0,1,0]
	v_fma_mix_f32 v89, v171, v232, v170 op_sel_hi:[0,1,0]
	v_fma_mix_f32 v84, v179, v206, v84 op_sel_hi:[0,1,0]
	v_fma_mix_f32 v85, v179, v214, v85 op_sel_hi:[0,1,0]
	v_fma_mix_f32 v68, v179, v224, v68 op_sel_hi:[0,1,0]
	v_fma_mix_f32 v89, v179, v236, v89 op_sel_hi:[0,1,0]
	v_fma_mix_f32 v84, v172, v200, v84 op_sel:[0,1,0] op_sel_hi:[0,1,0]
	v_fma_mix_f32 v85, v172, v210, v85 op_sel:[0,1,0] op_sel_hi:[0,1,0]
	v_fma_mix_f32 v68, v172, v218, v68 op_sel:[0,1,0] op_sel_hi:[0,1,0]
	v_fma_mix_f32 v89, v172, v232, v89 op_sel:[0,1,0] op_sel_hi:[0,1,0]
	v_fma_mix_f32 v84, v180, v206, v84 op_sel:[0,1,0] op_sel_hi:[0,1,0]
	v_fma_mix_f32 v85, v180, v214, v85 op_sel:[0,1,0] op_sel_hi:[0,1,0]
	v_fma_mix_f32 v68, v180, v224, v68 op_sel:[0,1,0] op_sel_hi:[0,1,0]
	v_fma_mix_f32 v89, v180, v236, v89 op_sel:[0,1,0] op_sel_hi:[0,1,0]
	v_fma_mix_f32 v84, v173, v201, v84 op_sel_hi:[0,1,0]
	v_fma_mix_f32 v85, v173, v211, v85 op_sel_hi:[0,1,0]
	v_fma_mix_f32 v68, v173, v219, v68 op_sel_hi:[0,1,0]
	v_fma_mix_f32 v89, v173, v233, v89 op_sel_hi:[0,1,0]
	v_fma_mix_f32 v84, v181, v207, v84 op_sel_hi:[0,1,0]
	v_fma_mix_f32 v85, v181, v215, v85 op_sel_hi:[0,1,0]
	v_fma_mix_f32 v68, v181, v225, v68 op_sel_hi:[0,1,0]
	v_fma_mix_f32 v89, v181, v237, v89 op_sel_hi:[0,1,0]
	v_fma_mix_f32 v84, v174, v201, v84 op_sel:[0,1,0] op_sel_hi:[0,1,0]
	v_fma_mix_f32 v85, v174, v211, v85 op_sel:[0,1,0] op_sel_hi:[0,1,0]
	v_fma_mix_f32 v68, v174, v219, v68 op_sel:[0,1,0] op_sel_hi:[0,1,0]
	v_fma_mix_f32 v89, v174, v233, v89 op_sel:[0,1,0] op_sel_hi:[0,1,0]
	v_fma_mix_f32 v84, v182, v207, v84 op_sel:[0,1,0] op_sel_hi:[0,1,0]
	v_fma_mix_f32 v85, v182, v215, v85 op_sel:[0,1,0] op_sel_hi:[0,1,0]
	v_fma_mix_f32 v68, v182, v225, v68 op_sel:[0,1,0] op_sel_hi:[0,1,0]
	v_fma_mix_f32 v89, v182, v237, v89 op_sel:[0,1,0] op_sel_hi:[0,1,0]
	v_fma_mix_f32 v84, v175, v202, v84 op_sel_hi:[0,1,0]
	v_fma_mix_f32 v85, v175, v212, v85 op_sel_hi:[0,1,0]
	v_fma_mix_f32 v68, v175, v220, v68 op_sel_hi:[0,1,0]
	v_fma_mix_f32 v89, v175, v234, v89 op_sel_hi:[0,1,0]
	v_fma_mix_f32 v84, v183, v208, v84 op_sel_hi:[0,1,0]
	v_fma_mix_f32 v85, v183, v216, v85 op_sel_hi:[0,1,0]
	v_fma_mix_f32 v68, v183, v226, v68 op_sel_hi:[0,1,0]
	v_fma_mix_f32 v89, v183, v238, v89 op_sel_hi:[0,1,0]
	v_fma_mix_f32 v84, v176, v202, v84 op_sel:[0,1,0] op_sel_hi:[0,1,0]
	v_fma_mix_f32 v85, v176, v212, v85 op_sel:[0,1,0] op_sel_hi:[0,1,0]
	v_fma_mix_f32 v68, v176, v220, v68 op_sel:[0,1,0] op_sel_hi:[0,1,0]
	v_fma_mix_f32 v89, v176, v234, v89 op_sel:[0,1,0] op_sel_hi:[0,1,0]
	v_fma_mix_f32 v84, v184, v208, v84 op_sel:[0,1,0] op_sel_hi:[0,1,0]
	v_fma_mix_f32 v85, v184, v216, v85 op_sel:[0,1,0] op_sel_hi:[0,1,0]
	v_fma_mix_f32 v68, v184, v226, v68 op_sel:[0,1,0] op_sel_hi:[0,1,0]
	v_fma_mix_f32 v89, v184, v238, v89 op_sel:[0,1,0] op_sel_hi:[0,1,0]
	v_fma_mix_f32 v84, v177, v203, v84 op_sel_hi:[0,1,0]
	v_fma_mix_f32 v85, v177, v213, v85 op_sel_hi:[0,1,0]
	v_fma_mix_f32 v68, v177, v221, v68 op_sel_hi:[0,1,0]
	v_fma_mix_f32 v89, v177, v235, v89 op_sel_hi:[0,1,0]
	v_fma_mix_f32 v84, v185, v209, v84 op_sel_hi:[0,1,0]
	v_fma_mix_f32 v85, v185, v217, v85 op_sel_hi:[0,1,0]
	v_fma_mix_f32 v68, v185, v227, v68 op_sel_hi:[0,1,0]
	v_fma_mix_f32 v89, v185, v239, v89 op_sel_hi:[0,1,0]
	v_fma_mix_f32 v84, v178, v203, v84 op_sel:[0,1,0] op_sel_hi:[0,1,0]
	v_fma_mix_f32 v85, v178, v213, v85 op_sel:[0,1,0] op_sel_hi:[0,1,0]
	v_fma_mix_f32 v68, v178, v221, v68 op_sel:[0,1,0] op_sel_hi:[0,1,0]
	v_fma_mix_f32 v89, v178, v235, v89 op_sel:[0,1,0] op_sel_hi:[0,1,0]
	v_fma_mix_f32 v84, v186, v209, v84 op_sel:[0,1,0] op_sel_hi:[0,1,0]
	v_fma_mix_f32 v85, v186, v217, v85 op_sel:[0,1,0] op_sel_hi:[0,1,0]
	v_fma_mix_f32 v68, v186, v227, v68 op_sel:[0,1,0] op_sel_hi:[0,1,0]
	v_fma_mix_f32 v89, v186, v239, v89 op_sel:[0,1,0] op_sel_hi:[0,1,0]
	v_mul_f32_e64 v241, |v84|, s86
	v_mul_f32_e64 v242, |v85|, s86
	v_mul_f32_e64 v243, |v68|, s86
	v_mul_f32_e64 v244, |v89|, s86
	v_exp_f32_e32 v241, v241
	v_exp_f32_e32 v242, v242
	v_exp_f32_e32 v243, v243
	v_exp_f32_e32 v244, v244
	v_add_f32_e32 v241, 1.0, v241
	v_add_f32_e32 v242, 1.0, v242
	v_add_f32_e32 v243, 1.0, v243
	v_add_f32_e32 v244, 1.0, v244
	v_log_f32_e32 v241, v241
	v_log_f32_e32 v242, v242
	v_log_f32_e32 v243, v243
	v_log_f32_e32 v244, v244
	v_mul_f32_e32 v245, 0x3f317217, v241
	v_mul_f32_e32 v246, 0x3f317217, v242
	v_mul_f32_e32 v247, 0x3f317217, v243
	v_mul_f32_e32 v248, 0x3f317217, v244
	v_fma_f32 v245, v241, s73, -v245
	v_fma_f32 v246, v242, s73, -v246
	v_fma_f32 v247, v243, s73, -v247
	v_fma_f32 v248, v244, s73, -v248
	v_fmac_f32_e32 v245, 0x3377d1cf, v241
	v_fmac_f32_e32 v246, 0x3377d1cf, v242
	v_fmac_f32_e32 v247, 0x3377d1cf, v243
	v_fmac_f32_e32 v248, 0x3377d1cf, v244
	v_fmac_f32_e32 v245, 0x3f317217, v241
	v_fmac_f32_e32 v246, 0x3f317217, v242
	v_fmac_f32_e32 v247, 0x3f317217, v243
	v_fmac_f32_e32 v248, 0x3f317217, v244
	v_min_f32_e32 v84, 0, v84
	v_min_f32_e32 v85, 0, v85
	v_min_f32_e32 v68, 0, v68
	v_min_f32_e32 v89, 0, v89
	v_sub_f32_e32 v84, v84, v245
	v_sub_f32_e32 v85, v85, v246
	v_sub_f32_e32 v68, v68, v247
	v_sub_f32_e32 v89, v89, v248
	v_mul_f32_e32 v84, 0x3d800000, v84
	v_mul_f32_e32 v85, 0x3d800000, v85
	v_mul_f32_e32 v68, 0x3d800000, v68
	v_mul_f32_e32 v89, 0x3d800000, v89
	s_andn2_b64 vcc, exec, s[34:35]
	s_cbranch_vccnz .LBB0_1565
	v_add_f32_e32 v90, v68, v89
	v_add_f32_e32 v82, v85, v90
	v_add_f32_e32 v83, v84, v82
	v_add_f32_e32 v86, v81, v83
	v_add_f32_e32 v87, v80, v86
	v_add_f32_e32 v91, v79, v87
	v_add_f32_e32 v92, v78, v91
	v_add_f32_e32 v95, v77, v92
	v_add_f32_e32 v88, v76, v95
	v_add_f32_e32 v96, v75, v88
	v_add_f32_e32 v97, v74, v96
	v_add_f32_e32 v98, v71, v97
	v_add_f32_e32 v99, v70, v98
	v_add_f32_e32 v100, v69, v99
	v_add_f32_e32 v93, v73, v100
	s_mov_b64 s[16:17], 0
